# HGRN2 next-chunk prefetch with running pointers instead of per-chunk 64-bit multiply-add address generation
# baseline (speedup 1.0000x reference)
.LBB0_1167:
	s_or_b64 exec, exec, s[0:1]
	s_lshl_b32 s36, s72, 7
	s_ashr_i32 s1, s3, 31
	v_readlane_b32 s0, v251, 10
	s_add_u32 s0, s0, s3
	v_readlane_b32 s3, v251, 11
	s_addc_u32 s1, s3, s1
	s_ashr_i32 s3, s2, 31
	s_lshl_b64 s[6:7], s[36:37], 2
	s_waitcnt lgkmcnt(0)
	s_add_u32 s6, s4, s6
	s_addc_u32 s7, s5, s7
	s_ashr_i32 s5, s8, 31
	s_add_u32 s4, s30, s8
	s_addc_u32 s5, s31, s5
	v_readlane_b32 s8, v254, 15
	s_add_u32 s2, s8, s2
	v_readlane_b32 s8, v254, 16
	v_lshlrev_b32_e32 v74, 1, v18
	s_addc_u32 s3, s8, s3
	v_ashrrev_i32_e32 v75, 31, v74
	v_lshl_add_u64 v[76:77], v[74:75], 2, s[2:3]
	v_readlane_b32 s2, v254, 39
	s_add_u32 s2, s0, s2
	v_readlane_b32 s3, v254, 38
	v_readlane_b32 s8, v254, 14
	s_addc_u32 s3, s1, s3
	s_lshl_b32 s36, s8, 1
	s_add_u32 s2, s2, s36
	s_addc_u32 s3, s3, 0
	v_lshl_add_u64 v[2:3], v[74:75], 1, s[2:3]
	s_mov_b64 s[2:3], 0x2000
	v_lshl_add_u64 v[78:79], v[2:3], 0, s[2:3]
	v_readlane_b32 s2, v254, 42
	v_mov_b64_e32 v[4:5], s[0:1]
	s_movk_i32 s11, 0x4000
	v_add_u32_e32 v6, s2, v18
	v_mad_i64_i32 v[4:5], s[2:3], v6, s28, v[4:5]
	v_add_co_u32_e32 v6, vcc, s66, v2
	s_movk_i32 s3, 0x2000
	s_nop 0
	v_addc_co_u32_e32 v7, vcc, 0, v3, vcc
	v_add_co_u32_e32 v8, vcc, s3, v76
	s_mov_b32 s3, 0x9000
	s_nop 0
	v_addc_co_u32_e32 v9, vcc, 0, v77, vcc
	v_add_co_u32_e32 v10, vcc, s3, v2
	s_mov_b32 s3, 0xf000
	s_nop 0
	v_addc_co_u32_e32 v11, vcc, 0, v3, vcc
	v_add_co_u32_e32 v12, vcc, s11, v76
	v_readlane_b32 s10, v254, 17
	s_nop 0
	v_addc_co_u32_e32 v13, vcc, 0, v77, vcc
	v_add_co_u32_e32 v14, vcc, s3, v2
	s_mov_b32 s3, 0x15000
	s_nop 0
	v_addc_co_u32_e32 v15, vcc, 0, v3, vcc
	v_add_co_u32_e32 v16, vcc, s28, v76
	s_lshl_b32 s8, s10, 1
	s_nop 0
	v_addc_co_u32_e32 v17, vcc, 0, v77, vcc
	v_add_co_u32_e32 v20, vcc, s3, v2
	s_mov_b32 s3, 0x8000
	s_nop 0
	v_addc_co_u32_e32 v21, vcc, 0, v3, vcc
	global_load_dword v75, v[6:7], off offset:-4096
	global_load_dword v125, v[6:7], off
	global_load_dword v126, v[10:11], off offset:-4096
	global_load_dword v127, v[10:11], off
	global_load_dword v128, v[14:15], off offset:-4096
	global_load_dword v129, v[14:15], off
	global_load_dword v130, v[20:21], off offset:-4096
	global_load_dword v131, v[20:21], off
	v_add_co_u32_e32 v6, vcc, s3, v76
	s_mov_b32 s3, 0x1b000
	s_nop 0
	v_addc_co_u32_e32 v7, vcc, 0, v77, vcc
	global_load_dwordx2 v[80:81], v[8:9], off
	global_load_dwordx2 v[82:83], v[12:13], off
	global_load_dwordx2 v[86:87], v[16:17], off
	global_load_dwordx2 v[90:91], v[6:7], off
	v_add_co_u32_e32 v6, vcc, s3, v2
	s_mov_b32 s3, 0xa000
	s_nop 0
	v_addc_co_u32_e32 v7, vcc, 0, v3, vcc
	v_add_co_u32_e32 v8, vcc, s3, v76
	s_mov_b32 s3, 0x21000
	s_nop 0
	v_addc_co_u32_e32 v9, vcc, 0, v77, vcc
	v_add_co_u32_e32 v10, vcc, s3, v2
	s_mov_b32 s3, 0xc000
	s_nop 0
	v_addc_co_u32_e32 v11, vcc, 0, v3, vcc
	v_add_co_u32_e32 v12, vcc, s3, v76
	s_mov_b32 s3, 0x27000
	s_nop 0
	v_addc_co_u32_e32 v13, vcc, 0, v77, vcc
	v_add_co_u32_e32 v14, vcc, s3, v2
	s_mov_b32 s3, 0xe000
	s_nop 0
	v_addc_co_u32_e32 v15, vcc, 0, v3, vcc
	v_add_co_u32_e32 v16, vcc, s3, v76
	s_mov_b32 s3, 0x2d000
	s_nop 0
	v_addc_co_u32_e32 v17, vcc, 0, v77, vcc
	v_add_co_u32_e32 v2, vcc, s3, v2
	global_load_dwordx2 v[96:97], v[8:9], off
	global_load_dwordx2 v[100:101], v[12:13], off
	global_load_dwordx2 v[102:103], v[16:17], off
	v_addc_co_u32_e32 v3, vcc, 0, v3, vcc
	global_load_dword v140, v[6:7], off offset:-4096
	global_load_dword v142, v[6:7], off
	global_load_dword v144, v[10:11], off offset:-4096
	global_load_dword v149, v[10:11], off
	global_load_dword v156, v[14:15], off offset:-4096
	global_load_dword v157, v[14:15], off
	global_load_dword v158, v[2:3], off offset:-4096
	global_load_dword v159, v[2:3], off
	v_lshl_add_u64 v[2:3], v[4:5], 0, s[36:37]
	s_mov_b32 s9, s37
	v_ashrrev_i32_e32 v19, 4, v18
	v_lshl_add_u64 v[2:3], v[2:3], 0, s[8:9]
	s_mov_b64 s[8:9], 0x4000
	v_lshl_add_u64 v[84:85], v[2:3], 0, s[8:9]
	v_add_co_u32_e32 v2, vcc, s11, v2
	v_lshlrev_b32_e32 v88, 2, v19
	s_nop 0
	v_addc_co_u32_e32 v3, vcc, 0, v3, vcc
	v_ashrrev_i32_e32 v89, 31, v88
	v_readlane_b32 s8, v254, 47
	global_load_dwordx4 v[22:25], v[2:3], off
	global_load_dwordx2 v[92:93], v[76:77], off
	global_load_dwordx4 v[26:29], v[84:85], off offset:16
	v_lshl_add_u64 v[2:3], v[88:89], 2, s[6:7]
	s_lshl_b32 s6, s8, 2
	s_mov_b32 s7, s37
	v_lshl_add_u64 v[14:15], v[2:3], 0, s[6:7]
	global_load_dwordx4 v[2:5], v[14:15], off
	global_load_dwordx4 v[6:9], v[14:15], off offset:64
	global_load_dwordx4 v[10:13], v[14:15], off offset:128
	s_nop 0
	global_load_dwordx4 v[14:17], v[14:15], off offset:192
	v_add_u32_e32 v0, 0, v0
	s_movk_i32 s3, 0x11c
	v_mad_u64_u32 v[20:21], s[6:7], v18, s3, v[0:1]
	v_and_b32_e32 v124, 15, v18
	v_readlane_b32 s7, v254, 25
	v_lshlrev_b32_e32 v132, 3, v18
	v_and_b32_e32 v133, -16, v18
	v_readlane_b32 s3, v254, 43
	s_movk_i32 s11, 0x90
	v_cmp_gt_u32_e64 s[86:87], 16, v18
	v_lshl_add_u32 v135, v18, 2, s7
	v_or_b32_e32 v18, s10, v124
	v_or_b32_e32 v30, s3, v124
	v_mul_lo_u32 v18, v18, s11
	v_mul_lo_u32 v31, v30, s11
	s_add_i32 s3, 0, 0x15c00
	s_add_i32 s6, 0, 0x18000
	v_add_u32_e32 v34, 0, v18
	v_add_u32_e32 v18, s10, v88
	v_sub_u32_e32 v21, v124, v88
	v_add_u32_e32 v31, s3, v31
	s_add_i32 s3, 0, 0x11400
	v_lshlrev_b32_e32 v35, 2, v18
	v_lshl_add_u32 v36, v18, 1, s6
	v_or_b32_e32 v18, s8, v124
	v_add_u32_e32 v32, s3, v133
	v_cmp_gt_i32_e64 s[88:89], 0, v21
	v_cmp_gt_i32_e64 s[90:91], 1, v21
	v_cmp_gt_i32_e64 s[92:93], 2, v21
	v_cmp_gt_i32_e64 s[94:95], 3, v21
	v_mul_u32_u24_e32 v21, 0x90, v18
	v_mul_u32_u24_e32 v37, 0x110, v18
	v_mov_b32_e32 v18, s3
	v_readlane_b32 s3, v254, 44
	v_mul_lo_u32 v30, v30, s29
	v_mad_u32_u24 v137, v124, s11, v18
	v_or_b32_e32 v138, s3, v124
	v_readlane_b32 s3, v255, 9
	v_readlane_b32 s9, v254, 48
	v_add_u32_e32 v30, 0, v30
	v_add_u32_e32 v33, s6, v133
	v_readlane_b32 s7, v254, 24
	v_add_u32_e32 v38, 0x1200, v137
	v_add_u32_e32 v39, 0x2400, v137
	v_add_u32_e32 v40, 0x3600, v137
	v_add_u32_e32 v94, s8, v88
	v_mul_u32_u24_e32 v41, 0x110, v124
	v_lshl_add_u32 v139, v19, 3, s3
	v_readlane_b32 s3, v255, 10
	v_mov_b32_e32 v18, 0
	v_add_u32_e32 v19, 0, v35
	s_mov_b32 s2, 0
	v_add_u32_e32 v134, 0, v133
	v_lshl_add_u32 v136, v124, 2, s7
	v_ashrrev_i32_e32 v95, 31, v94
	v_lshl_add_u64 v[98:99], v[88:89], 0, s[8:9]
	v_add3_u32 v141, v41, v133, s3
	v_add_u32_e32 v143, s10, v20
	v_add_u32_e32 v145, v31, v133
	v_add_u32_e32 v146, v30, v133
	v_add_u32_e32 v147, v32, v21
	v_add_u32_e32 v148, v33, v37
	v_add_u32_e32 v150, v34, v133
	v_add_u32_e32 v151, 0x20800, v19
	v_add_u32_e32 v152, v38, v133
	v_add_u32_e32 v153, v39, v133
	v_add_u32_e32 v154, v40, v133
	v_add_u32_e32 v155, v36, v41
	v_mov_b32_e32 v19, v18
	v_mov_b32_e32 v20, v18
	v_mov_b32_e32 v21, v18
	v_mov_b32_e32 v30, v18
	v_mov_b32_e32 v31, v18
	v_mov_b32_e32 v32, v18
	v_mov_b32_e32 v33, v18
	v_mov_b32_e32 v34, v18
	v_mov_b32_e32 v35, v18
	v_mov_b32_e32 v36, v18
	v_mov_b32_e32 v37, v18
	v_mov_b32_e32 v38, v18
	v_mov_b32_e32 v39, v18
	v_mov_b32_e32 v40, v18
	v_mov_b32_e32 v41, v18
	v_mov_b32_e32 v42, v18
	v_mov_b32_e32 v43, v18
	v_mov_b32_e32 v44, v18
	v_mov_b32_e32 v45, v18
	v_mov_b32_e32 v50, v18
	v_mov_b32_e32 v51, v18
	v_mov_b32_e32 v52, v18
	v_mov_b32_e32 v53, v18
	v_mov_b32_e32 v46, v18
	v_mov_b32_e32 v47, v18
	v_mov_b32_e32 v48, v18
	v_mov_b32_e32 v49, v18
	v_mov_b32_e32 v54, v18
	v_mov_b32_e32 v55, v18
	v_mov_b32_e32 v56, v18
	v_mov_b32_e32 v57, v18
	s_mov_b64 vcc, 0x80000
	v_lshl_add_u64 v[214:215], v[76:77], 0, vcc
	s_mov_b64 vcc, 0x2000
	v_lshl_add_u64 v[216:217], v[214:215], 0, vcc
	v_lshl_add_u64 v[218:219], v[216:217], 0, vcc
	v_lshl_add_u64 v[220:221], v[218:219], 0, vcc
	v_lshl_add_u64 v[222:223], v[220:221], 0, vcc
	v_lshl_add_u64 v[224:225], v[222:223], 0, vcc
	v_lshl_add_u64 v[226:227], v[224:225], 0, vcc
	v_lshl_add_u64 v[228:229], v[226:227], 0, vcc
	s_mov_b64 vcc, 0x180800
	v_lshl_add_u64 v[230:231], v[78:79], 0, vcc
	s_mov_b64 vcc, 0x6000
	v_lshl_add_u64 v[232:233], v[230:231], 0, vcc
	v_lshl_add_u64 v[234:235], v[232:233], 0, vcc
	v_lshl_add_u64 v[236:237], v[234:235], 0, vcc
	v_lshl_add_u64 v[238:239], v[236:237], 0, vcc
	v_lshl_add_u64 v[240:241], v[238:239], 0, vcc
	v_lshl_add_u64 v[242:243], v[240:241], 0, vcc
	v_lshl_add_u64 v[244:245], v[242:243], 0, vcc
	s_mov_b64 vcc, 0x180000
	v_lshl_add_u64 v[246:247], v[84:85], 0, vcc
	s_barrier
	s_branch .LBB0_1169

.LBB0_1173:
	v_readlane_b32 s6, v254, 18
	v_readlane_b32 s7, v254, 19
	s_mul_i32 s3, s20, 0x880
	s_nop 0
	v_cndmask_b32_e64 v123, v123, 0, s[6:7]
	v_cndmask_b32_e64 v122, v122, 0, s[6:7]
	v_readlane_b32 s6, v254, 26
	v_pk_add_f32 v[72:73], v[72:73], v[122:123]
	v_readlane_b32 s7, v254, 27
	s_nop 1
	v_cndmask_b32_e64 v73, v123, v73, s[6:7]
	v_cndmask_b32_e64 v72, v122, v72, s[6:7]
	v_readlane_b32 s6, v254, 28
	v_pk_add_f32 v[66:67], v[66:67], v[72:73]
	v_readlane_b32 s7, v254, 29
	s_nop 1
	v_cndmask_b32_e64 v67, v73, v67, s[6:7]
	v_cndmask_b32_e64 v66, v72, v66, s[6:7]
	v_readlane_b32 s6, v254, 30
	v_pk_add_f32 v[68:69], v[68:69], v[66:67]
	v_readlane_b32 s7, v254, 31
	s_nop 1
	v_cndmask_b32_e64 v67, v67, v69, s[6:7]
	v_cndmask_b32_e64 v66, v66, v68, s[6:7]
	v_readlane_b32 s6, v254, 32
	v_pk_add_f32 v[62:63], v[62:63], v[66:67]
	v_readlane_b32 s7, v254, 33
	v_and_b32_e32 v69, 0xffff0000, v125
	v_lshlrev_b32_e32 v68, 16, v125
	v_cndmask_b32_e64 v63, v67, v63, s[6:7]
	v_cndmask_b32_e64 v62, v66, v62, s[6:7]
	v_readlane_b32 s6, v254, 34
	v_pk_add_f32 v[64:65], v[64:65], v[62:63]
	v_readlane_b32 s7, v254, 35
	v_lshlrev_b32_e32 v66, 16, v75
	v_and_b32_e32 v67, 0xffff0000, v75
	v_cndmask_b32_e64 v63, v63, v65, s[6:7]
	v_cndmask_b32_e64 v62, v62, v64, s[6:7]
	v_readlane_b32 s6, v254, 36
	v_pk_add_f32 v[58:59], v[58:59], v[62:63]
	v_readlane_b32 s7, v254, 37
	s_nop 1
	v_cndmask_b32_e64 v59, v63, v59, s[6:7]
	v_cndmask_b32_e64 v58, v62, v58, s[6:7]
	v_readlane_b32 s6, v254, 40
	v_pk_add_f32 v[60:61], v[60:61], v[58:59]
	v_readlane_b32 s7, v254, 41
	s_nop 1
	v_cndmask_b32_e64 v58, v58, v60, s[6:7]
	v_sub_f32_e32 v60, v120, v70
	v_cndmask_b32_e64 v59, v59, v61, s[6:7]
	v_exp_f32_e32 v64, v60
	v_sub_f32_e32 v60, v121, v71
	v_exp_f32_e32 v65, v60
	v_pk_add_f32 v[60:61], v[118:119], v[58:59]
	s_nop 0
	v_pk_add_f32 v[62:63], v[60:61], v[70:71] neg_lo:[0,1] neg_hi:[0,1]
	v_exp_f32_e32 v60, v60
	v_min_f32_e32 v73, 0x42e60000, v63
	v_min_f32_e64 v63, -v63, s14
	v_min_f32_e32 v72, 0x42e60000, v62
	v_min_f32_e64 v62, -v62, s14
	v_exp_f32_e32 v63, v63
	v_exp_f32_e32 v72, v72
	v_exp_f32_e32 v73, v73
	v_exp_f32_e32 v62, v62
	v_exp_f32_e32 v61, v61
	v_mul_f32_e32 v63, v63, v69
	v_add_u32_e32 v69, s3, v0
	v_mul_f32_e32 v60, v60, v66
	v_mul_f32_e32 v72, v72, v66
	v_mul_f32_e32 v73, v73, v67
	v_mul_f32_e32 v62, v62, v68
	v_cvt_pk_bf16_f32 v68, v72, v73
	ds_write_b32 v69, v68
	v_mul_f32_e32 v61, v61, v67
	v_cvt_pk_bf16_f32 v60, v60, v61
	ds_write_b32 v69, v60 offset:17408
	v_cvt_pk_bf16_f32 v60, v62, v63
	ds_write_b32 v69, v60 offset:34816
	v_pk_add_f32 v[60:61], v[116:117], v[58:59]
	v_mul_f32_e32 v66, v64, v62
	v_mul_f32_e32 v67, v63, v65
	v_pk_add_f32 v[62:63], v[60:61], v[70:71] neg_lo:[0,1] neg_hi:[0,1]
	v_exp_f32_e32 v60, v60
	v_min_f32_e32 v117, 0x42e60000, v62
	v_min_f32_e32 v118, 0x42e60000, v63
	v_min_f32_e64 v62, -v62, s14
	v_exp_f32_e32 v117, v117
	v_exp_f32_e32 v118, v118
	v_exp_f32_e32 v62, v62
	v_min_f32_e64 v63, -v63, s14
	v_exp_f32_e32 v61, v61
	v_exp_f32_e32 v63, v63
	v_lshlrev_b32_e32 v68, 16, v126
	v_and_b32_e32 v72, 0xffff0000, v126
	v_lshlrev_b32_e32 v73, 16, v127
	v_mul_f32_e32 v60, v60, v68
	v_and_b32_e32 v116, 0xffff0000, v127
	v_mul_f32_e32 v117, v117, v68
	v_mul_f32_e32 v118, v118, v72
	v_mul_f32_e32 v62, v62, v73
	v_cvt_pk_bf16_f32 v73, v117, v118
	ds_write_b32 v69, v73 offset:272
	v_mul_f32_e32 v61, v61, v72
	v_cvt_pk_bf16_f32 v60, v60, v61
	v_mul_f32_e32 v63, v63, v116
	ds_write_b32 v69, v60 offset:17680
	v_cvt_pk_bf16_f32 v60, v62, v63
	ds_write_b32 v69, v60 offset:35088
	v_pk_add_f32 v[60:61], v[114:115], v[58:59]
	v_mul_f32_e32 v68, v64, v62
	v_mul_f32_e32 v72, v63, v65
	v_pk_add_f32 v[62:63], v[60:61], v[70:71] neg_lo:[0,1] neg_hi:[0,1]
	v_exp_f32_e32 v60, v60
	v_min_f32_e32 v117, 0x42e60000, v62
	v_min_f32_e32 v118, 0x42e60000, v63
	v_min_f32_e64 v62, -v62, s14
	v_exp_f32_e32 v117, v117
	v_exp_f32_e32 v118, v118
	v_exp_f32_e32 v62, v62
	v_min_f32_e64 v63, -v63, s14
	v_exp_f32_e32 v61, v61
	v_exp_f32_e32 v63, v63
	v_lshlrev_b32_e32 v73, 16, v128
	v_and_b32_e32 v114, 0xffff0000, v128
	v_lshlrev_b32_e32 v115, 16, v129
	v_mul_f32_e32 v60, v60, v73
	v_and_b32_e32 v116, 0xffff0000, v129
	v_mul_f32_e32 v117, v117, v73
	v_mul_f32_e32 v118, v118, v114
	v_mul_f32_e32 v62, v62, v115
	v_cvt_pk_bf16_f32 v115, v117, v118
	ds_write_b32 v69, v115 offset:544
	v_mul_f32_e32 v61, v61, v114
	v_cvt_pk_bf16_f32 v60, v60, v61
	v_mul_f32_e32 v63, v63, v116
	ds_write_b32 v69, v60 offset:17952
	v_cvt_pk_bf16_f32 v60, v62, v63
	ds_write_b32 v69, v60 offset:35360
	v_pk_add_f32 v[60:61], v[112:113], v[58:59]
	v_mul_f32_e32 v73, v64, v62
	v_mul_f32_e32 v114, v63, v65
	v_pk_add_f32 v[62:63], v[60:61], v[70:71] neg_lo:[0,1] neg_hi:[0,1]
	v_exp_f32_e32 v60, v60
	v_min_f32_e32 v117, 0x42e60000, v62
	v_min_f32_e32 v118, 0x42e60000, v63
	v_min_f32_e64 v62, -v62, s14
	v_exp_f32_e32 v117, v117
	v_exp_f32_e32 v118, v118
	v_exp_f32_e32 v62, v62
	v_min_f32_e64 v63, -v63, s14
	v_exp_f32_e32 v61, v61
	v_exp_f32_e32 v63, v63
	v_lshlrev_b32_e32 v112, 16, v130
	v_and_b32_e32 v113, 0xffff0000, v130
	v_lshlrev_b32_e32 v115, 16, v131
	v_mul_f32_e32 v60, v60, v112
	v_and_b32_e32 v116, 0xffff0000, v131
	v_mul_f32_e32 v117, v117, v112
	v_mul_f32_e32 v118, v118, v113
	v_mul_f32_e32 v62, v62, v115
	v_cvt_pk_bf16_f32 v115, v117, v118
	ds_write_b32 v69, v115 offset:816
	v_mul_f32_e32 v61, v61, v113
	v_cvt_pk_bf16_f32 v60, v60, v61
	v_mul_f32_e32 v63, v63, v116
	ds_write_b32 v69, v60 offset:18224
	v_cvt_pk_bf16_f32 v60, v62, v63
	ds_write_b32 v69, v60 offset:35632
	v_pk_add_f32 v[60:61], v[110:111], v[58:59]
	v_mul_f32_e32 v112, v64, v62
	v_mul_f32_e32 v113, v63, v65
	v_pk_add_f32 v[62:63], v[60:61], v[70:71] neg_lo:[0,1] neg_hi:[0,1]
	v_exp_f32_e32 v60, v60
	v_min_f32_e32 v117, 0x42e60000, v62
	v_min_f32_e32 v118, 0x42e60000, v63
	v_min_f32_e64 v62, -v62, s14
	v_exp_f32_e32 v117, v117
	v_exp_f32_e32 v118, v118
	v_exp_f32_e32 v62, v62
	v_min_f32_e64 v63, -v63, s14
	v_exp_f32_e32 v61, v61
	v_exp_f32_e32 v63, v63
	v_lshlrev_b32_e32 v110, 16, v140
	v_and_b32_e32 v111, 0xffff0000, v140
	v_lshlrev_b32_e32 v115, 16, v142
	v_mul_f32_e32 v60, v60, v110
	v_and_b32_e32 v116, 0xffff0000, v142
	v_mul_f32_e32 v117, v117, v110
	v_mul_f32_e32 v118, v118, v111
	v_mul_f32_e32 v62, v62, v115
	v_cvt_pk_bf16_f32 v115, v117, v118
	ds_write_b32 v69, v115 offset:1088
	v_mul_f32_e32 v61, v61, v111
	v_cvt_pk_bf16_f32 v60, v60, v61
	v_mul_f32_e32 v63, v63, v116
	ds_write_b32 v69, v60 offset:18496
	v_cvt_pk_bf16_f32 v60, v62, v63
	ds_write_b32 v69, v60 offset:35904
	v_pk_add_f32 v[60:61], v[108:109], v[58:59]
	v_mul_f32_e32 v110, v64, v62
	v_mul_f32_e32 v111, v63, v65
	v_pk_add_f32 v[62:63], v[60:61], v[70:71] neg_lo:[0,1] neg_hi:[0,1]
	v_exp_f32_e32 v60, v60
	v_min_f32_e32 v117, 0x42e60000, v62
	v_min_f32_e32 v118, 0x42e60000, v63
	v_min_f32_e64 v62, -v62, s14
	v_exp_f32_e32 v117, v117
	v_exp_f32_e32 v118, v118
	v_exp_f32_e32 v62, v62
	v_min_f32_e64 v63, -v63, s14
	v_exp_f32_e32 v61, v61
	v_exp_f32_e32 v63, v63
	v_lshlrev_b32_e32 v108, 16, v144
	v_and_b32_e32 v109, 0xffff0000, v144
	v_lshlrev_b32_e32 v115, 16, v149
	v_mul_f32_e32 v60, v60, v108
	v_and_b32_e32 v116, 0xffff0000, v149
	v_mul_f32_e32 v117, v117, v108
	v_mul_f32_e32 v118, v118, v109
	v_mul_f32_e32 v62, v62, v115
	v_cvt_pk_bf16_f32 v115, v117, v118
	ds_write_b32 v69, v115 offset:1360
	v_mul_f32_e32 v61, v61, v109
	v_cvt_pk_bf16_f32 v60, v60, v61
	v_mul_f32_e32 v63, v63, v116
	ds_write_b32 v69, v60 offset:18768
	v_cvt_pk_bf16_f32 v60, v62, v63
	ds_write_b32 v69, v60 offset:36176
	v_pk_add_f32 v[60:61], v[106:107], v[58:59]
	v_mul_f32_e32 v108, v64, v62
	v_mul_f32_e32 v109, v63, v65
	v_pk_add_f32 v[62:63], v[60:61], v[70:71] neg_lo:[0,1] neg_hi:[0,1]
	v_exp_f32_e32 v60, v60
	v_min_f32_e32 v117, 0x42e60000, v62
	v_min_f32_e32 v118, 0x42e60000, v63
	v_min_f32_e64 v62, -v62, s14
	v_exp_f32_e32 v117, v117
	v_exp_f32_e32 v118, v118
	v_exp_f32_e32 v62, v62
	v_min_f32_e64 v63, -v63, s14
	v_exp_f32_e32 v61, v61
	v_exp_f32_e32 v63, v63
	v_lshlrev_b32_e32 v106, 16, v156
	v_and_b32_e32 v107, 0xffff0000, v156
	v_lshlrev_b32_e32 v115, 16, v157
	v_mul_f32_e32 v60, v60, v106
	v_and_b32_e32 v116, 0xffff0000, v157
	v_mul_f32_e32 v117, v117, v106
	v_mul_f32_e32 v118, v118, v107
	v_mul_f32_e32 v62, v62, v115
	v_cvt_pk_bf16_f32 v115, v117, v118
	ds_write_b32 v69, v115 offset:1632
	v_mul_f32_e32 v61, v61, v107
	v_cvt_pk_bf16_f32 v60, v60, v61
	v_mul_f32_e32 v63, v63, v116
	ds_write_b32 v69, v60 offset:19040
	v_cvt_pk_bf16_f32 v60, v62, v63
	v_pk_add_f32 v[58:59], v[104:105], v[58:59]
	ds_write_b32 v69, v60 offset:36448
	v_pk_add_f32 v[60:61], v[58:59], v[70:71] neg_lo:[0,1] neg_hi:[0,1]
	v_exp_f32_e32 v58, v58
	v_min_f32_e32 v106, 0x42e60000, v60
	v_min_f32_e32 v107, 0x42e60000, v61
	v_min_f32_e64 v60, -v60, s14
	v_exp_f32_e32 v106, v106
	v_exp_f32_e32 v107, v107
	v_exp_f32_e32 v60, v60
	v_min_f32_e64 v61, -v61, s14
	v_exp_f32_e32 v59, v59
	v_exp_f32_e32 v61, v61
	v_lshlrev_b32_e32 v70, 16, v158
	v_and_b32_e32 v71, 0xffff0000, v158
	v_lshlrev_b32_e32 v104, 16, v159
	v_mul_f32_e32 v58, v58, v70
	v_and_b32_e32 v105, 0xffff0000, v159
	v_mul_f32_e32 v106, v106, v70
	v_mul_f32_e32 v107, v107, v71
	v_mul_f32_e32 v60, v60, v104
	v_cvt_pk_bf16_f32 v104, v106, v107
	ds_write_b32 v69, v104 offset:1904
	v_mul_f32_e32 v59, v59, v71
	v_cvt_pk_bf16_f32 v58, v58, v59
	v_mul_f32_e32 v61, v61, v105
	ds_write_b32 v69, v58 offset:19312
	v_cvt_pk_bf16_f32 v58, v60, v61
	ds_write_b32 v69, v58 offset:36720
	v_cvt_pk_bf16_f32 v58, v66, v68
	v_mul_f32_e32 v62, v64, v62
	v_mul_f32_e32 v63, v63, v65
	v_mul_f32_e32 v64, v64, v60
	v_mul_f32_e32 v65, v61, v65
	v_cvt_pk_bf16_f32 v59, v73, v112
	v_cvt_pk_bf16_f32 v60, v110, v108
	v_cvt_pk_bf16_f32 v61, v62, v64
	ds_write_b128 v143, v[58:61] offset:52224
	v_cvt_pk_bf16_f32 v58, v67, v72
	s_add_i32 s3, s2, 1
	v_cvt_pk_bf16_f32 v59, v114, v113
	v_cvt_pk_bf16_f32 v60, v111, v109
	v_cvt_pk_bf16_f32 v61, v63, v65
	ds_write_b128 v143, v[58:61] offset:52368
	v_add_u32_e32 v58, s19, v74
	s_cmp_eq_u32 s2, 31
	ds_write_b16 v58, v22
	ds_write_b16_d16_hi v58, v22 offset:144
	ds_write_b16 v58, v23 offset:288
	ds_write_b16_d16_hi v58, v23 offset:432
	ds_write_b16 v58, v24 offset:576
	ds_write_b16_d16_hi v58, v24 offset:720
	ds_write_b16 v58, v25 offset:864
	ds_write_b16_d16_hi v58, v25 offset:1008
	s_waitcnt vmcnt(4)
	ds_write_b16 v58, v26 offset:1152
	ds_write_b16_d16_hi v58, v26 offset:1296
	ds_write_b16 v58, v27 offset:1440
	ds_write_b16_d16_hi v58, v27 offset:1584
	ds_write_b16 v58, v28 offset:1728
	ds_write_b16_d16_hi v58, v28 offset:1872
	ds_write_b16 v58, v29 offset:2016
	ds_write_b16_d16_hi v58, v29 offset:2160
	s_cbranch_scc1 .LBB0_1175
	global_load_dwordx2 v[92:93], v[214:215], off
	global_load_dword v75, v[230:231], off offset:-2048
	global_load_dword v125, v[230:231], off offset:2048
	global_load_dwordx2 v[80:81], v[216:217], off
	global_load_dword v126, v[232:233], off offset:-2048
	global_load_dword v127, v[232:233], off offset:2048
	global_load_dwordx2 v[82:83], v[218:219], off
	global_load_dword v128, v[234:235], off offset:-2048
	global_load_dword v129, v[234:235], off offset:2048
	global_load_dwordx2 v[86:87], v[220:221], off
	global_load_dword v130, v[236:237], off offset:-2048
	global_load_dword v131, v[236:237], off offset:2048
	global_load_dwordx2 v[90:91], v[222:223], off
	global_load_dword v140, v[238:239], off offset:-2048
	global_load_dword v142, v[238:239], off offset:2048
	global_load_dwordx2 v[96:97], v[224:225], off
	global_load_dword v144, v[240:241], off offset:-2048
	global_load_dword v149, v[240:241], off offset:2048
	global_load_dwordx2 v[100:101], v[226:227], off
	global_load_dword v156, v[242:243], off offset:-2048
	global_load_dword v157, v[242:243], off offset:2048
	global_load_dwordx2 v[102:103], v[228:229], off
	global_load_dword v158, v[244:245], off offset:-2048
	global_load_dword v159, v[244:245], off offset:2048
	global_load_dwordx4 v[22:25], v[246:247], off
	global_load_dwordx4 v[26:29], v[246:247], off offset:16
	s_mov_b64 s[6:7], 0x80000
	v_lshl_add_u64 v[214:215], v[214:215], 0, s[6:7]
	v_lshl_add_u64 v[216:217], v[216:217], 0, s[6:7]
	v_lshl_add_u64 v[218:219], v[218:219], 0, s[6:7]
	v_lshl_add_u64 v[220:221], v[220:221], 0, s[6:7]
	v_lshl_add_u64 v[222:223], v[222:223], 0, s[6:7]
	v_lshl_add_u64 v[224:225], v[224:225], 0, s[6:7]
	v_lshl_add_u64 v[226:227], v[226:227], 0, s[6:7]
	v_lshl_add_u64 v[228:229], v[228:229], 0, s[6:7]
	s_mov_b64 s[6:7], 0x180000
	v_lshl_add_u64 v[230:231], v[230:231], 0, s[6:7]
	v_lshl_add_u64 v[232:233], v[232:233], 0, s[6:7]
	v_lshl_add_u64 v[234:235], v[234:235], 0, s[6:7]
	v_lshl_add_u64 v[236:237], v[236:237], 0, s[6:7]
	v_lshl_add_u64 v[238:239], v[238:239], 0, s[6:7]
	v_lshl_add_u64 v[240:241], v[240:241], 0, s[6:7]
	v_lshl_add_u64 v[242:243], v[242:243], 0, s[6:7]
	v_lshl_add_u64 v[244:245], v[244:245], 0, s[6:7]
	v_lshl_add_u64 v[246:247], v[246:247], 0, s[6:7]
